# retention scan: the state-update MFMAs (kd.v) fused into the A.v LDS stream (each v fragment read once, three MFMAs), separate s-part removed
# baseline (speedup 1.0000x reference)
.Lscan_noprio:
.Lscan_chunk:
	global_load_dwordx4 v[176:179], v194, s[66:67]
	global_load_dwordx4 v[180:183], v194, s[66:67] offset:128
	ds_read_b128 v[144:147], v196 offset:0
	ds_read_b128 v[148:151], v196 offset:8448
	ds_read_b128 v[152:155], v196 offset:16896
	ds_read_b128 v[156:159], v196 offset:25344
	ds_read_b128 v[160:163], v196 offset:64
	ds_read_b128 v[164:167], v196 offset:8512
	ds_read_b128 v[168:171], v196 offset:16960
	s_waitcnt lgkmcnt(6)
	s_waitcnt vmcnt(47)
	v_mfma_f32_16x16x32_bf16 v[112:115], v[144:147], v[0:3], 0
	ds_read_b128 v[172:175], v196 offset:25408
	s_waitcnt lgkmcnt(6)
	v_mfma_f32_16x16x32_bf16 v[116:119], v[148:151], v[0:3], 0
	ds_read_b128 v[144:147], v196 offset:128
	s_waitcnt lgkmcnt(6)
	v_mfma_f32_16x16x32_bf16 v[120:123], v[152:155], v[0:3], 0
	ds_read_b128 v[148:151], v196 offset:8576
	s_waitcnt lgkmcnt(6)
	v_mfma_f32_16x16x32_bf16 v[124:127], v[156:159], v[0:3], 0
	global_load_dwordx4 v[0:3], v193, s[60:61]
	ds_read_b128 v[152:155], v196 offset:17024
	s_waitcnt lgkmcnt(6)
	s_waitcnt vmcnt(47)
	v_mfma_f32_16x16x32_bf16 v[112:115], v[160:163], v[4:7], v[112:115]
	ds_read_b128 v[156:159], v196 offset:25472
	s_waitcnt lgkmcnt(6)
	v_mfma_f32_16x16x32_bf16 v[116:119], v[164:167], v[4:7], v[116:119]
	ds_read_b128 v[160:163], v196 offset:192
	s_waitcnt lgkmcnt(6)
	v_mfma_f32_16x16x32_bf16 v[120:123], v[168:171], v[4:7], v[120:123]
	ds_read_b128 v[164:167], v196 offset:8640
	s_waitcnt lgkmcnt(6)
	v_mfma_f32_16x16x32_bf16 v[124:127], v[172:175], v[4:7], v[124:127]
	global_load_dwordx4 v[4:7], v193, s[60:61] offset:64
	ds_read_b128 v[168:171], v196 offset:17088
	s_waitcnt lgkmcnt(6)
	s_waitcnt vmcnt(47)
	v_mfma_f32_16x16x32_bf16 v[112:115], v[144:147], v[8:11], v[112:115]
	ds_read_b128 v[172:175], v196 offset:25536
	s_waitcnt lgkmcnt(6)
	v_mfma_f32_16x16x32_bf16 v[116:119], v[148:151], v[8:11], v[116:119]
	ds_read_b128 v[144:147], v196 offset:256
	s_waitcnt lgkmcnt(6)
	v_mfma_f32_16x16x32_bf16 v[120:123], v[152:155], v[8:11], v[120:123]
	ds_read_b128 v[148:151], v196 offset:8704
	s_waitcnt lgkmcnt(6)
	v_mfma_f32_16x16x32_bf16 v[124:127], v[156:159], v[8:11], v[124:127]
	global_load_dwordx4 v[8:11], v193, s[60:61] offset:128
	ds_read_b128 v[152:155], v196 offset:17152
	s_waitcnt lgkmcnt(6)
	s_waitcnt vmcnt(47)
	v_mfma_f32_16x16x32_bf16 v[112:115], v[160:163], v[12:15], v[112:115]
	ds_read_b128 v[156:159], v196 offset:25600
	s_waitcnt lgkmcnt(6)
	v_mfma_f32_16x16x32_bf16 v[116:119], v[164:167], v[12:15], v[116:119]
	ds_read_b128 v[160:163], v196 offset:320
	s_waitcnt lgkmcnt(6)
	v_mfma_f32_16x16x32_bf16 v[120:123], v[168:171], v[12:15], v[120:123]
	ds_read_b128 v[164:167], v196 offset:8768
	s_waitcnt lgkmcnt(6)
	v_mfma_f32_16x16x32_bf16 v[124:127], v[172:175], v[12:15], v[124:127]
	global_load_dwordx4 v[12:15], v193, s[60:61] offset:192
	ds_read_b128 v[168:171], v196 offset:17216
	s_waitcnt lgkmcnt(6)
	s_waitcnt vmcnt(47)
	v_mfma_f32_16x16x32_bf16 v[112:115], v[144:147], v[16:19], v[112:115]
	ds_read_b128 v[172:175], v196 offset:25664
	s_waitcnt lgkmcnt(6)
	v_mfma_f32_16x16x32_bf16 v[116:119], v[148:151], v[16:19], v[116:119]
	ds_read_b128 v[144:147], v196 offset:384
	s_waitcnt lgkmcnt(6)
	v_mfma_f32_16x16x32_bf16 v[120:123], v[152:155], v[16:19], v[120:123]
	ds_read_b128 v[148:151], v196 offset:8832
	s_waitcnt lgkmcnt(6)
	v_mfma_f32_16x16x32_bf16 v[124:127], v[156:159], v[16:19], v[124:127]
	global_load_dwordx4 v[16:19], v193, s[60:61] offset:256
	ds_read_b128 v[152:155], v196 offset:17280
	s_waitcnt lgkmcnt(6)
	s_waitcnt vmcnt(47)
	v_mfma_f32_16x16x32_bf16 v[112:115], v[160:163], v[20:23], v[112:115]
	ds_read_b128 v[156:159], v196 offset:25728
	s_waitcnt lgkmcnt(6)
	v_mfma_f32_16x16x32_bf16 v[116:119], v[164:167], v[20:23], v[116:119]
	ds_read_b128 v[160:163], v196 offset:448
	s_waitcnt lgkmcnt(6)
	v_mfma_f32_16x16x32_bf16 v[120:123], v[168:171], v[20:23], v[120:123]
	ds_read_b128 v[164:167], v196 offset:8896
	s_waitcnt lgkmcnt(6)
	v_mfma_f32_16x16x32_bf16 v[124:127], v[172:175], v[20:23], v[124:127]
	global_load_dwordx4 v[20:23], v193, s[60:61] offset:320
	ds_read_b128 v[168:171], v196 offset:17344
	s_waitcnt lgkmcnt(6)
	s_waitcnt vmcnt(47)
	v_mfma_f32_16x16x32_bf16 v[112:115], v[144:147], v[24:27], v[112:115]
	ds_read_b128 v[172:175], v196 offset:25792
	s_waitcnt lgkmcnt(6)
	v_mfma_f32_16x16x32_bf16 v[116:119], v[148:151], v[24:27], v[116:119]
	s_waitcnt lgkmcnt(5)
	v_mfma_f32_16x16x32_bf16 v[120:123], v[152:155], v[24:27], v[120:123]
	s_waitcnt lgkmcnt(4)
	v_mfma_f32_16x16x32_bf16 v[124:127], v[156:159], v[24:27], v[124:127]
	global_load_dwordx4 v[24:27], v193, s[60:61] offset:384
	s_waitcnt lgkmcnt(3)
	s_waitcnt vmcnt(47)
	v_mfma_f32_16x16x32_bf16 v[112:115], v[160:163], v[28:31], v[112:115]
	s_waitcnt lgkmcnt(2)
	v_mfma_f32_16x16x32_bf16 v[116:119], v[164:167], v[28:31], v[116:119]
	s_waitcnt lgkmcnt(1)
	v_mfma_f32_16x16x32_bf16 v[120:123], v[168:171], v[28:31], v[120:123]
	s_waitcnt lgkmcnt(0)
	v_mfma_f32_16x16x32_bf16 v[124:127], v[172:175], v[28:31], v[124:127]
	global_load_dwordx4 v[28:31], v193, s[60:61] offset:448
	s_nop 7
	v_pk_mul_f32 v[112:113], v[112:113], v[202:203]
	v_pk_mul_f32 v[114:115], v[114:115], v[202:203]
	v_pk_mul_f32 v[116:117], v[116:117], v[202:203]
	v_pk_mul_f32 v[118:119], v[118:119], v[202:203]
	v_pk_mul_f32 v[120:121], v[120:121], v[202:203]
	v_pk_mul_f32 v[122:123], v[122:123], v[202:203]
	v_pk_mul_f32 v[124:125], v[124:125], v[202:203]
	v_pk_mul_f32 v[126:127], v[126:127], v[202:203]
	v_pk_mul_f32 v[80:81], v[80:81], v[204:205]
	v_pk_mul_f32 v[82:83], v[82:83], v[204:205]
	v_pk_mul_f32 v[84:85], v[84:85], v[204:205]
	v_pk_mul_f32 v[86:87], v[86:87], v[204:205]
	v_pk_mul_f32 v[88:89], v[88:89], v[204:205]
	v_pk_mul_f32 v[90:91], v[90:91], v[204:205]
	v_pk_mul_f32 v[92:93], v[92:93], v[204:205]
	v_pk_mul_f32 v[94:95], v[94:95], v[204:205]
	v_pk_mul_f32 v[96:97], v[96:97], v[204:205]
	v_pk_mul_f32 v[98:99], v[98:99], v[204:205]
	v_pk_mul_f32 v[100:101], v[100:101], v[204:205]
	v_pk_mul_f32 v[102:103], v[102:103], v[204:205]
	v_pk_mul_f32 v[104:105], v[104:105], v[204:205]
	v_pk_mul_f32 v[106:107], v[106:107], v[204:205]
	v_pk_mul_f32 v[108:109], v[108:109], v[204:205]
	v_pk_mul_f32 v[110:111], v[110:111], v[204:205]
	ds_read_b128 v[144:147], v197 offset:0
	ds_read_b128 v[148:151], v197 offset:4352
	ds_read_b128 v[152:155], v197 offset:8704
	ds_read_b128 v[156:159], v197 offset:13056
	ds_read_b128 v[160:163], v197 offset:64
	ds_read_b128 v[164:167], v197 offset:4416
	ds_read_b128 v[168:171], v197 offset:8768
	s_waitcnt lgkmcnt(6)
	s_waitcnt vmcnt(21)
	v_mfma_f32_16x16x32_bf16 v[112:115], v[144:147], v[32:35], v[112:115]
	v_mfma_f32_16x16x32_bf16 v[80:83], v[48:51], v[144:147], v[80:83]
	v_mfma_f32_16x16x32_bf16 v[96:99], v[64:67], v[144:147], v[96:99]
	ds_read_b128 v[172:175], v197 offset:13120
	s_waitcnt lgkmcnt(6)
	v_mfma_f32_16x16x32_bf16 v[116:119], v[148:151], v[32:35], v[116:119]
	v_mfma_f32_16x16x32_bf16 v[84:87], v[48:51], v[148:151], v[84:87]
	v_mfma_f32_16x16x32_bf16 v[100:103], v[64:67], v[148:151], v[100:103]
	ds_read_b128 v[144:147], v197 offset:128
	s_waitcnt lgkmcnt(6)
	v_mfma_f32_16x16x32_bf16 v[120:123], v[152:155], v[32:35], v[120:123]
	v_mfma_f32_16x16x32_bf16 v[88:91], v[48:51], v[152:155], v[88:91]
	v_mfma_f32_16x16x32_bf16 v[104:107], v[64:67], v[152:155], v[104:107]
	ds_read_b128 v[148:151], v197 offset:4480
	s_waitcnt lgkmcnt(6)
	v_mfma_f32_16x16x32_bf16 v[124:127], v[156:159], v[32:35], v[124:127]
	v_mfma_f32_16x16x32_bf16 v[92:95], v[48:51], v[156:159], v[92:95]
	v_mfma_f32_16x16x32_bf16 v[108:111], v[64:67], v[156:159], v[108:111]
	global_load_dwordx4 v[32:35], v192, s[62:63]
	global_load_dwordx4 v[48:51], v192, s[64:65] offset:-4096
	global_load_dwordx4 v[64:67], v192, s[64:65]
	ds_read_b128 v[152:155], v197 offset:8832
	s_waitcnt lgkmcnt(6)
	s_waitcnt vmcnt(21)
	v_mfma_f32_16x16x32_bf16 v[112:115], v[160:163], v[36:39], v[112:115]
	v_mfma_f32_16x16x32_bf16 v[80:83], v[52:55], v[160:163], v[80:83]
	v_mfma_f32_16x16x32_bf16 v[96:99], v[68:71], v[160:163], v[96:99]
	ds_read_b128 v[156:159], v197 offset:13184
	s_waitcnt lgkmcnt(6)
	v_mfma_f32_16x16x32_bf16 v[116:119], v[164:167], v[36:39], v[116:119]
	v_mfma_f32_16x16x32_bf16 v[84:87], v[52:55], v[164:167], v[84:87]
	v_mfma_f32_16x16x32_bf16 v[100:103], v[68:71], v[164:167], v[100:103]
	ds_read_b128 v[160:163], v197 offset:192
	s_waitcnt lgkmcnt(6)
	v_mfma_f32_16x16x32_bf16 v[120:123], v[168:171], v[36:39], v[120:123]
	v_mfma_f32_16x16x32_bf16 v[88:91], v[52:55], v[168:171], v[88:91]
	v_mfma_f32_16x16x32_bf16 v[104:107], v[68:71], v[168:171], v[104:107]
	ds_read_b128 v[164:167], v197 offset:4544
	s_waitcnt lgkmcnt(6)
	v_mfma_f32_16x16x32_bf16 v[124:127], v[172:175], v[36:39], v[124:127]
	v_mfma_f32_16x16x32_bf16 v[92:95], v[52:55], v[172:175], v[92:95]
	v_mfma_f32_16x16x32_bf16 v[108:111], v[68:71], v[172:175], v[108:111]
	global_load_dwordx4 v[36:39], v192, s[62:63] offset:1024
	global_load_dwordx4 v[52:55], v192, s[64:65] offset:-3072
	global_load_dwordx4 v[68:71], v192, s[64:65] offset:1024
	ds_read_b128 v[168:171], v197 offset:8896
	s_waitcnt lgkmcnt(6)
	s_waitcnt vmcnt(21)
	v_mfma_f32_16x16x32_bf16 v[112:115], v[144:147], v[40:43], v[112:115]
	v_mfma_f32_16x16x32_bf16 v[80:83], v[56:59], v[144:147], v[80:83]
	v_mfma_f32_16x16x32_bf16 v[96:99], v[72:75], v[144:147], v[96:99]
	ds_read_b128 v[172:175], v197 offset:13248
	s_waitcnt lgkmcnt(6)
	v_mfma_f32_16x16x32_bf16 v[116:119], v[148:151], v[40:43], v[116:119]
	v_mfma_f32_16x16x32_bf16 v[84:87], v[56:59], v[148:151], v[84:87]
	v_mfma_f32_16x16x32_bf16 v[100:103], v[72:75], v[148:151], v[100:103]
	s_waitcnt lgkmcnt(5)
	v_mfma_f32_16x16x32_bf16 v[120:123], v[152:155], v[40:43], v[120:123]
	v_mfma_f32_16x16x32_bf16 v[88:91], v[56:59], v[152:155], v[88:91]
	v_mfma_f32_16x16x32_bf16 v[104:107], v[72:75], v[152:155], v[104:107]
	s_waitcnt lgkmcnt(4)
	v_mfma_f32_16x16x32_bf16 v[124:127], v[156:159], v[40:43], v[124:127]
	v_mfma_f32_16x16x32_bf16 v[92:95], v[56:59], v[156:159], v[92:95]
	v_mfma_f32_16x16x32_bf16 v[108:111], v[72:75], v[156:159], v[108:111]
	global_load_dwordx4 v[40:43], v192, s[62:63] offset:2048
	global_load_dwordx4 v[56:59], v192, s[64:65] offset:-2048
	global_load_dwordx4 v[72:75], v192, s[64:65] offset:2048
	s_waitcnt lgkmcnt(3)
	s_waitcnt vmcnt(21)
	v_mfma_f32_16x16x32_bf16 v[112:115], v[160:163], v[44:47], v[112:115]
	v_mfma_f32_16x16x32_bf16 v[80:83], v[60:63], v[160:163], v[80:83]
	v_mfma_f32_16x16x32_bf16 v[96:99], v[76:79], v[160:163], v[96:99]
	s_waitcnt lgkmcnt(2)
	v_mfma_f32_16x16x32_bf16 v[116:119], v[164:167], v[44:47], v[116:119]
	v_mfma_f32_16x16x32_bf16 v[84:87], v[60:63], v[164:167], v[84:87]
	v_mfma_f32_16x16x32_bf16 v[100:103], v[76:79], v[164:167], v[100:103]
	s_waitcnt lgkmcnt(1)
	v_mfma_f32_16x16x32_bf16 v[120:123], v[168:171], v[44:47], v[120:123]
	v_mfma_f32_16x16x32_bf16 v[88:91], v[60:63], v[168:171], v[88:91]
	v_mfma_f32_16x16x32_bf16 v[104:107], v[76:79], v[168:171], v[104:107]
	s_waitcnt lgkmcnt(0)
	v_mfma_f32_16x16x32_bf16 v[124:127], v[172:175], v[44:47], v[124:127]
	v_mfma_f32_16x16x32_bf16 v[92:95], v[60:63], v[172:175], v[92:95]
	v_mfma_f32_16x16x32_bf16 v[108:111], v[76:79], v[172:175], v[108:111]
	global_load_dwordx4 v[44:47], v192, s[62:63] offset:3072
	global_load_dwordx4 v[60:63], v192, s[64:65] offset:-1024
	global_load_dwordx4 v[76:79], v192, s[64:65] offset:3072
	s_nop 7
	v_cvt_pk_bf16_f32 v160, v112, v113
	v_cvt_pk_bf16_f32 v161, v114, v115
	v_cvt_pk_bf16_f32 v162, v116, v117
	v_cvt_pk_bf16_f32 v163, v118, v119
	v_cvt_pk_bf16_f32 v164, v120, v121
	v_cvt_pk_bf16_f32 v165, v122, v123
	v_cvt_pk_bf16_f32 v166, v124, v125
	v_cvt_pk_bf16_f32 v167, v126, v127
	ds_write_b64 v214, v[160:161]
	ds_write_b64 v214, v[162:163] offset:32
	ds_write_b64 v214, v[164:165] offset:64
	ds_write_b64 v214, v[166:167] offset:96
	s_waitcnt lgkmcnt(0)
	ds_read_b128 v[144:147], v215
	ds_read_b128 v[148:151], v215 offset:1152
	s_waitcnt lgkmcnt(0)
	global_store_dwordx4 v195, v[144:147], s[68:69]
	global_store_dwordx4 v220, v[148:151], s[68:69]
	v_cvt_pk_bf16_f32 v144, v80, v81
	v_cvt_pk_bf16_f32 v145, v82, v83
	ds_write_b64 v200, v[144:145] offset:0
	v_cvt_pk_bf16_f32 v148, v84, v85
	v_cvt_pk_bf16_f32 v149, v86, v87
	ds_write_b64 v200, v[148:149] offset:8448
	v_cvt_pk_bf16_f32 v152, v88, v89
	v_cvt_pk_bf16_f32 v153, v90, v91
	ds_write_b64 v200, v[152:153] offset:16896
	v_cvt_pk_bf16_f32 v156, v92, v93
	v_cvt_pk_bf16_f32 v157, v94, v95
	ds_write_b64 v200, v[156:157] offset:25344
	v_cvt_pk_bf16_f32 v160, v96, v97
	v_cvt_pk_bf16_f32 v161, v98, v99
	ds_write_b64 v200, v[160:161] offset:32
	v_cvt_pk_bf16_f32 v164, v100, v101
	v_cvt_pk_bf16_f32 v165, v102, v103
	ds_write_b64 v200, v[164:165] offset:8480
	v_cvt_pk_bf16_f32 v168, v104, v105
	v_cvt_pk_bf16_f32 v169, v106, v107
	ds_write_b64 v200, v[168:169] offset:16928
	v_cvt_pk_bf16_f32 v172, v108, v109
	v_cvt_pk_bf16_f32 v173, v110, v111
	ds_write_b64 v200, v[172:173] offset:25376
	s_waitcnt vmcnt(46)
	ds_write_b128 v201, v[222:225]
	ds_write_b128 v201, v[226:229] offset:128
	v_add_u32_e32 v196, s80, v196
	v_subrev_u32_e32 v200, s80, v200
	v_add_u32_e32 v197, s81, v197
	v_subrev_u32_e32 v201, s81, v201
	s_sub_u32 s80, 0, s80
	s_sub_u32 s81, 0, s81
	s_add_u32 s68, s68, 0x80000
	s_addc_u32 s69, s69, 0
	s_add_u32 s70, s70, 1
	s_cmp_lt_u32 s70, 31
	s_cselect_b32 s83, 1, 0
	s_lshl_b32 s76, s83, 16
	s_add_u32 s64, s64, s76
	s_addc_u32 s65, s65, 0
	s_cmp_lt_u32 s70, 30
	s_cselect_b32 s83, 1, 0
	s_lshl_b32 s76, s83, 18
	s_add_u32 s60, s60, s76
	s_addc_u32 s61, s61, 0
	s_lshl_b32 s76, s83, 15
	s_add_u32 s62, s62, s76
	s_addc_u32 s63, s63, 0
	s_lshl_b32 s76, s83, 8
	s_add_u32 s66, s66, s76
	s_addc_u32 s67, s67, 0
	s_waitcnt lgkmcnt(0)
	s_barrier
	global_load_dwordx4 v[222:225], v194, s[66:67]
	global_load_dwordx4 v[226:229], v194, s[66:67] offset:128
	ds_read_b128 v[144:147], v196 offset:0
	ds_read_b128 v[148:151], v196 offset:8448
	ds_read_b128 v[152:155], v196 offset:16896
	ds_read_b128 v[156:159], v196 offset:25344
	ds_read_b128 v[160:163], v196 offset:64
	ds_read_b128 v[164:167], v196 offset:8512
	ds_read_b128 v[168:171], v196 offset:16960
	s_waitcnt lgkmcnt(6)
	s_waitcnt vmcnt(47)
	v_mfma_f32_16x16x32_bf16 v[112:115], v[144:147], v[230:233], 0
	ds_read_b128 v[172:175], v196 offset:25408
	s_waitcnt lgkmcnt(6)
	v_mfma_f32_16x16x32_bf16 v[116:119], v[148:151], v[230:233], 0
	ds_read_b128 v[144:147], v196 offset:128
	s_waitcnt lgkmcnt(6)
	v_mfma_f32_16x16x32_bf16 v[120:123], v[152:155], v[230:233], 0
	ds_read_b128 v[148:151], v196 offset:8576
	s_waitcnt lgkmcnt(6)
	v_mfma_f32_16x16x32_bf16 v[124:127], v[156:159], v[230:233], 0
	global_load_dwordx4 v[230:233], v193, s[60:61]
	ds_read_b128 v[152:155], v196 offset:17024
	s_waitcnt lgkmcnt(6)
	s_waitcnt vmcnt(47)
	v_mfma_f32_16x16x32_bf16 v[112:115], v[160:163], v[234:237], v[112:115]
	ds_read_b128 v[156:159], v196 offset:25472
	s_waitcnt lgkmcnt(6)
	v_mfma_f32_16x16x32_bf16 v[116:119], v[164:167], v[234:237], v[116:119]
	ds_read_b128 v[160:163], v196 offset:192
	s_waitcnt lgkmcnt(6)
	v_mfma_f32_16x16x32_bf16 v[120:123], v[168:171], v[234:237], v[120:123]
	ds_read_b128 v[164:167], v196 offset:8640
	s_waitcnt lgkmcnt(6)
	v_mfma_f32_16x16x32_bf16 v[124:127], v[172:175], v[234:237], v[124:127]
	global_load_dwordx4 v[234:237], v193, s[60:61] offset:64
	ds_read_b128 v[168:171], v196 offset:17088
	s_waitcnt lgkmcnt(6)
	s_waitcnt vmcnt(47)
	v_mfma_f32_16x16x32_bf16 v[112:115], v[144:147], v[238:241], v[112:115]
	ds_read_b128 v[172:175], v196 offset:25536
	s_waitcnt lgkmcnt(6)
	v_mfma_f32_16x16x32_bf16 v[116:119], v[148:151], v[238:241], v[116:119]
	ds_read_b128 v[144:147], v196 offset:256
	s_waitcnt lgkmcnt(6)
	v_mfma_f32_16x16x32_bf16 v[120:123], v[152:155], v[238:241], v[120:123]
	ds_read_b128 v[148:151], v196 offset:8704
	s_waitcnt lgkmcnt(6)
	v_mfma_f32_16x16x32_bf16 v[124:127], v[156:159], v[238:241], v[124:127]
	global_load_dwordx4 v[238:241], v193, s[60:61] offset:128
	ds_read_b128 v[152:155], v196 offset:17152
	s_waitcnt lgkmcnt(6)
	s_waitcnt vmcnt(47)
	v_mfma_f32_16x16x32_bf16 v[112:115], v[160:163], v[242:245], v[112:115]
	ds_read_b128 v[156:159], v196 offset:25600
	s_waitcnt lgkmcnt(6)
	v_mfma_f32_16x16x32_bf16 v[116:119], v[164:167], v[242:245], v[116:119]
	ds_read_b128 v[160:163], v196 offset:320
	s_waitcnt lgkmcnt(6)
	v_mfma_f32_16x16x32_bf16 v[120:123], v[168:171], v[242:245], v[120:123]
	ds_read_b128 v[164:167], v196 offset:8768
	s_waitcnt lgkmcnt(6)
	v_mfma_f32_16x16x32_bf16 v[124:127], v[172:175], v[242:245], v[124:127]
	global_load_dwordx4 v[242:245], v193, s[60:61] offset:192
	ds_read_b128 v[168:171], v196 offset:17216
	s_waitcnt lgkmcnt(6)
	s_waitcnt vmcnt(47)
	v_mfma_f32_16x16x32_bf16 v[112:115], v[144:147], v[246:249], v[112:115]
	ds_read_b128 v[172:175], v196 offset:25664
	s_waitcnt lgkmcnt(6)
	v_mfma_f32_16x16x32_bf16 v[116:119], v[148:151], v[246:249], v[116:119]
	ds_read_b128 v[144:147], v196 offset:384
	s_waitcnt lgkmcnt(6)
	v_mfma_f32_16x16x32_bf16 v[120:123], v[152:155], v[246:249], v[120:123]
	ds_read_b128 v[148:151], v196 offset:8832
	s_waitcnt lgkmcnt(6)
	v_mfma_f32_16x16x32_bf16 v[124:127], v[156:159], v[246:249], v[124:127]
	global_load_dwordx4 v[246:249], v193, s[60:61] offset:256
	ds_read_b128 v[152:155], v196 offset:17280
	s_waitcnt lgkmcnt(6)
	s_waitcnt vmcnt(47)
	v_mfma_f32_16x16x32_bf16 v[112:115], v[160:163], v[250:253], v[112:115]
	ds_read_b128 v[156:159], v196 offset:25728
	s_waitcnt lgkmcnt(6)
	v_mfma_f32_16x16x32_bf16 v[116:119], v[164:167], v[250:253], v[116:119]
	ds_read_b128 v[160:163], v196 offset:448
	s_waitcnt lgkmcnt(6)
	v_mfma_f32_16x16x32_bf16 v[120:123], v[168:171], v[250:253], v[120:123]
	ds_read_b128 v[164:167], v196 offset:8896
	s_waitcnt lgkmcnt(6)
	v_mfma_f32_16x16x32_bf16 v[124:127], v[172:175], v[250:253], v[124:127]
	global_load_dwordx4 v[250:253], v193, s[60:61] offset:320
	ds_read_b128 v[168:171], v196 offset:17344
	s_waitcnt lgkmcnt(6)
	s_waitcnt vmcnt(47)
	v_mfma_f32_16x16x32_bf16 v[112:115], v[144:147], v[184:187], v[112:115]
	ds_read_b128 v[172:175], v196 offset:25792
	s_waitcnt lgkmcnt(6)
	v_mfma_f32_16x16x32_bf16 v[116:119], v[148:151], v[184:187], v[116:119]
	s_waitcnt lgkmcnt(5)
	v_mfma_f32_16x16x32_bf16 v[120:123], v[152:155], v[184:187], v[120:123]
	s_waitcnt lgkmcnt(4)
	v_mfma_f32_16x16x32_bf16 v[124:127], v[156:159], v[184:187], v[124:127]
	global_load_dwordx4 v[184:187], v193, s[60:61] offset:384
	s_waitcnt lgkmcnt(3)
	s_waitcnt vmcnt(47)
	v_mfma_f32_16x16x32_bf16 v[112:115], v[160:163], v[188:191], v[112:115]
	s_waitcnt lgkmcnt(2)
	v_mfma_f32_16x16x32_bf16 v[116:119], v[164:167], v[188:191], v[116:119]
	s_waitcnt lgkmcnt(1)
	v_mfma_f32_16x16x32_bf16 v[120:123], v[168:171], v[188:191], v[120:123]
	s_waitcnt lgkmcnt(0)
	v_mfma_f32_16x16x32_bf16 v[124:127], v[172:175], v[188:191], v[124:127]
	global_load_dwordx4 v[188:191], v193, s[60:61] offset:448
	s_nop 7
	v_pk_mul_f32 v[112:113], v[112:113], v[202:203]
	v_pk_mul_f32 v[114:115], v[114:115], v[202:203]
	v_pk_mul_f32 v[116:117], v[116:117], v[202:203]
	v_pk_mul_f32 v[118:119], v[118:119], v[202:203]
	v_pk_mul_f32 v[120:121], v[120:121], v[202:203]
	v_pk_mul_f32 v[122:123], v[122:123], v[202:203]
	v_pk_mul_f32 v[124:125], v[124:125], v[202:203]
	v_pk_mul_f32 v[126:127], v[126:127], v[202:203]
	v_pk_mul_f32 v[80:81], v[80:81], v[204:205]
	v_pk_mul_f32 v[82:83], v[82:83], v[204:205]
	v_pk_mul_f32 v[84:85], v[84:85], v[204:205]
	v_pk_mul_f32 v[86:87], v[86:87], v[204:205]
	v_pk_mul_f32 v[88:89], v[88:89], v[204:205]
	v_pk_mul_f32 v[90:91], v[90:91], v[204:205]
	v_pk_mul_f32 v[92:93], v[92:93], v[204:205]
	v_pk_mul_f32 v[94:95], v[94:95], v[204:205]
	v_pk_mul_f32 v[96:97], v[96:97], v[204:205]
	v_pk_mul_f32 v[98:99], v[98:99], v[204:205]
	v_pk_mul_f32 v[100:101], v[100:101], v[204:205]
	v_pk_mul_f32 v[102:103], v[102:103], v[204:205]
	v_pk_mul_f32 v[104:105], v[104:105], v[204:205]
	v_pk_mul_f32 v[106:107], v[106:107], v[204:205]
	v_pk_mul_f32 v[108:109], v[108:109], v[204:205]
	v_pk_mul_f32 v[110:111], v[110:111], v[204:205]
	ds_read_b128 v[144:147], v197 offset:0
	ds_read_b128 v[148:151], v197 offset:4352
	ds_read_b128 v[152:155], v197 offset:8704
	ds_read_b128 v[156:159], v197 offset:13056
	ds_read_b128 v[160:163], v197 offset:64
	ds_read_b128 v[164:167], v197 offset:4416
	ds_read_b128 v[168:171], v197 offset:8768
	s_waitcnt lgkmcnt(6)
	s_waitcnt vmcnt(21)
	v_mfma_f32_16x16x32_bf16 v[112:115], v[144:147], v[128:131], v[112:115]
	v_mfma_f32_16x16x32_bf16 v[80:83], v[48:51], v[144:147], v[80:83]
	v_mfma_f32_16x16x32_bf16 v[96:99], v[64:67], v[144:147], v[96:99]
	ds_read_b128 v[172:175], v197 offset:13120
	s_waitcnt lgkmcnt(6)
	v_mfma_f32_16x16x32_bf16 v[116:119], v[148:151], v[128:131], v[116:119]
	v_mfma_f32_16x16x32_bf16 v[84:87], v[48:51], v[148:151], v[84:87]
	v_mfma_f32_16x16x32_bf16 v[100:103], v[64:67], v[148:151], v[100:103]
	ds_read_b128 v[144:147], v197 offset:128
	s_waitcnt lgkmcnt(6)
	v_mfma_f32_16x16x32_bf16 v[120:123], v[152:155], v[128:131], v[120:123]
	v_mfma_f32_16x16x32_bf16 v[88:91], v[48:51], v[152:155], v[88:91]
	v_mfma_f32_16x16x32_bf16 v[104:107], v[64:67], v[152:155], v[104:107]
	ds_read_b128 v[148:151], v197 offset:4480
	s_waitcnt lgkmcnt(6)
	v_mfma_f32_16x16x32_bf16 v[124:127], v[156:159], v[128:131], v[124:127]
	v_mfma_f32_16x16x32_bf16 v[92:95], v[48:51], v[156:159], v[92:95]
	v_mfma_f32_16x16x32_bf16 v[108:111], v[64:67], v[156:159], v[108:111]
	global_load_dwordx4 v[128:131], v192, s[62:63]
	global_load_dwordx4 v[48:51], v192, s[64:65] offset:-4096
	global_load_dwordx4 v[64:67], v192, s[64:65]
	ds_read_b128 v[152:155], v197 offset:8832
	s_waitcnt lgkmcnt(6)
	s_waitcnt vmcnt(21)
	v_mfma_f32_16x16x32_bf16 v[112:115], v[160:163], v[132:135], v[112:115]
	v_mfma_f32_16x16x32_bf16 v[80:83], v[52:55], v[160:163], v[80:83]
	v_mfma_f32_16x16x32_bf16 v[96:99], v[68:71], v[160:163], v[96:99]
	ds_read_b128 v[156:159], v197 offset:13184
	s_waitcnt lgkmcnt(6)
	v_mfma_f32_16x16x32_bf16 v[116:119], v[164:167], v[132:135], v[116:119]
	v_mfma_f32_16x16x32_bf16 v[84:87], v[52:55], v[164:167], v[84:87]
	v_mfma_f32_16x16x32_bf16 v[100:103], v[68:71], v[164:167], v[100:103]
	ds_read_b128 v[160:163], v197 offset:192
	s_waitcnt lgkmcnt(6)
	v_mfma_f32_16x16x32_bf16 v[120:123], v[168:171], v[132:135], v[120:123]
	v_mfma_f32_16x16x32_bf16 v[88:91], v[52:55], v[168:171], v[88:91]
	v_mfma_f32_16x16x32_bf16 v[104:107], v[68:71], v[168:171], v[104:107]
	ds_read_b128 v[164:167], v197 offset:4544
	s_waitcnt lgkmcnt(6)
	v_mfma_f32_16x16x32_bf16 v[124:127], v[172:175], v[132:135], v[124:127]
	v_mfma_f32_16x16x32_bf16 v[92:95], v[52:55], v[172:175], v[92:95]
	v_mfma_f32_16x16x32_bf16 v[108:111], v[68:71], v[172:175], v[108:111]
	global_load_dwordx4 v[132:135], v192, s[62:63] offset:1024
	global_load_dwordx4 v[52:55], v192, s[64:65] offset:-3072
	global_load_dwordx4 v[68:71], v192, s[64:65] offset:1024
	ds_read_b128 v[168:171], v197 offset:8896
	s_waitcnt lgkmcnt(6)
	s_waitcnt vmcnt(21)
	v_mfma_f32_16x16x32_bf16 v[112:115], v[144:147], v[136:139], v[112:115]
	v_mfma_f32_16x16x32_bf16 v[80:83], v[56:59], v[144:147], v[80:83]
	v_mfma_f32_16x16x32_bf16 v[96:99], v[72:75], v[144:147], v[96:99]
	ds_read_b128 v[172:175], v197 offset:13248
	s_waitcnt lgkmcnt(6)
	v_mfma_f32_16x16x32_bf16 v[116:119], v[148:151], v[136:139], v[116:119]
	v_mfma_f32_16x16x32_bf16 v[84:87], v[56:59], v[148:151], v[84:87]
	v_mfma_f32_16x16x32_bf16 v[100:103], v[72:75], v[148:151], v[100:103]
	s_waitcnt lgkmcnt(5)
	v_mfma_f32_16x16x32_bf16 v[120:123], v[152:155], v[136:139], v[120:123]
	v_mfma_f32_16x16x32_bf16 v[88:91], v[56:59], v[152:155], v[88:91]
	v_mfma_f32_16x16x32_bf16 v[104:107], v[72:75], v[152:155], v[104:107]
	s_waitcnt lgkmcnt(4)
	v_mfma_f32_16x16x32_bf16 v[124:127], v[156:159], v[136:139], v[124:127]
	v_mfma_f32_16x16x32_bf16 v[92:95], v[56:59], v[156:159], v[92:95]
	v_mfma_f32_16x16x32_bf16 v[108:111], v[72:75], v[156:159], v[108:111]
	global_load_dwordx4 v[136:139], v192, s[62:63] offset:2048
	global_load_dwordx4 v[56:59], v192, s[64:65] offset:-2048
	global_load_dwordx4 v[72:75], v192, s[64:65] offset:2048
	s_waitcnt lgkmcnt(3)
	s_waitcnt vmcnt(21)
	v_mfma_f32_16x16x32_bf16 v[112:115], v[160:163], v[140:143], v[112:115]
	v_mfma_f32_16x16x32_bf16 v[80:83], v[60:63], v[160:163], v[80:83]
	v_mfma_f32_16x16x32_bf16 v[96:99], v[76:79], v[160:163], v[96:99]
	s_waitcnt lgkmcnt(2)
	v_mfma_f32_16x16x32_bf16 v[116:119], v[164:167], v[140:143], v[116:119]
	v_mfma_f32_16x16x32_bf16 v[84:87], v[60:63], v[164:167], v[84:87]
	v_mfma_f32_16x16x32_bf16 v[100:103], v[76:79], v[164:167], v[100:103]
	s_waitcnt lgkmcnt(1)
	v_mfma_f32_16x16x32_bf16 v[120:123], v[168:171], v[140:143], v[120:123]
	v_mfma_f32_16x16x32_bf16 v[88:91], v[60:63], v[168:171], v[88:91]
	v_mfma_f32_16x16x32_bf16 v[104:107], v[76:79], v[168:171], v[104:107]
	s_waitcnt lgkmcnt(0)
	v_mfma_f32_16x16x32_bf16 v[124:127], v[172:175], v[140:143], v[124:127]
	v_mfma_f32_16x16x32_bf16 v[92:95], v[60:63], v[172:175], v[92:95]
	v_mfma_f32_16x16x32_bf16 v[108:111], v[76:79], v[172:175], v[108:111]
	global_load_dwordx4 v[140:143], v192, s[62:63] offset:3072
	global_load_dwordx4 v[60:63], v192, s[64:65] offset:-1024
	global_load_dwordx4 v[76:79], v192, s[64:65] offset:3072
	s_nop 7
	v_cvt_pk_bf16_f32 v160, v112, v113
	v_cvt_pk_bf16_f32 v161, v114, v115
	v_cvt_pk_bf16_f32 v162, v116, v117
	v_cvt_pk_bf16_f32 v163, v118, v119
	v_cvt_pk_bf16_f32 v164, v120, v121
	v_cvt_pk_bf16_f32 v165, v122, v123
	v_cvt_pk_bf16_f32 v166, v124, v125
	v_cvt_pk_bf16_f32 v167, v126, v127
	ds_write_b64 v214, v[160:161]
	ds_write_b64 v214, v[162:163] offset:32
	ds_write_b64 v214, v[164:165] offset:64
	ds_write_b64 v214, v[166:167] offset:96
	s_waitcnt lgkmcnt(0)
	ds_read_b128 v[144:147], v215
	ds_read_b128 v[148:151], v215 offset:1152
	s_waitcnt lgkmcnt(0)
	global_store_dwordx4 v195, v[144:147], s[68:69]
	global_store_dwordx4 v220, v[148:151], s[68:69]
	v_cvt_pk_bf16_f32 v144, v80, v81
	v_cvt_pk_bf16_f32 v145, v82, v83
	ds_write_b64 v200, v[144:145] offset:0
	v_cvt_pk_bf16_f32 v148, v84, v85
	v_cvt_pk_bf16_f32 v149, v86, v87
	ds_write_b64 v200, v[148:149] offset:8448
	v_cvt_pk_bf16_f32 v152, v88, v89
	v_cvt_pk_bf16_f32 v153, v90, v91
	ds_write_b64 v200, v[152:153] offset:16896
	v_cvt_pk_bf16_f32 v156, v92, v93
	v_cvt_pk_bf16_f32 v157, v94, v95
	ds_write_b64 v200, v[156:157] offset:25344
	v_cvt_pk_bf16_f32 v160, v96, v97
	v_cvt_pk_bf16_f32 v161, v98, v99
	ds_write_b64 v200, v[160:161] offset:32
	v_cvt_pk_bf16_f32 v164, v100, v101
	v_cvt_pk_bf16_f32 v165, v102, v103
	ds_write_b64 v200, v[164:165] offset:8480
	v_cvt_pk_bf16_f32 v168, v104, v105
	v_cvt_pk_bf16_f32 v169, v106, v107
	ds_write_b64 v200, v[168:169] offset:16928
	v_cvt_pk_bf16_f32 v172, v108, v109
	v_cvt_pk_bf16_f32 v173, v110, v111
	ds_write_b64 v200, v[172:173] offset:25376
	s_waitcnt vmcnt(46)
	ds_write_b128 v201, v[176:179]
	ds_write_b128 v201, v[180:183] offset:128
	v_add_u32_e32 v196, s80, v196
	v_subrev_u32_e32 v200, s80, v200
	v_add_u32_e32 v197, s81, v197
	v_subrev_u32_e32 v201, s81, v201
	s_sub_u32 s80, 0, s80
	s_sub_u32 s81, 0, s81
	s_add_u32 s68, s68, 0x80000
	s_addc_u32 s69, s69, 0
	s_add_u32 s70, s70, 1
	s_cmp_lt_u32 s70, 31
	s_cselect_b32 s83, 1, 0
	s_lshl_b32 s76, s83, 16
	s_add_u32 s64, s64, s76
	s_addc_u32 s65, s65, 0
	s_cmp_lt_u32 s70, 30
	s_cselect_b32 s83, 1, 0
	s_lshl_b32 s76, s83, 18
	s_add_u32 s60, s60, s76
	s_addc_u32 s61, s61, 0
	s_lshl_b32 s76, s83, 15
	s_add_u32 s62, s62, s76
	s_addc_u32 s63, s63, 0
	s_lshl_b32 s76, s83, 8
	s_add_u32 s66, s66, s76
	s_addc_u32 s67, s67, 0
	s_waitcnt lgkmcnt(0)
	s_barrier
	s_cmp_lt_u32 s70, 32
	s_cbranch_scc1 .Lscan_chunk
	s_setprio 0
	s_waitcnt vmcnt(0)
	global_store_dword v206, v80, s[44:45]
	global_store_dword v207, v81, s[44:45]
	global_store_dword v208, v82, s[44:45]
	global_store_dword v209, v83, s[44:45]
	global_store_dword v206, v84, s[44:45] offset:64
	global_store_dword v207, v85, s[44:45] offset:64
	global_store_dword v208, v86, s[44:45] offset:64
	global_store_dword v209, v87, s[44:45] offset:64
	global_store_dword v206, v88, s[44:45] offset:128
	global_store_dword v207, v89, s[44:45] offset:128
	global_store_dword v208, v90, s[44:45] offset:128
	global_store_dword v209, v91, s[44:45] offset:128
	global_store_dword v206, v92, s[44:45] offset:192
	global_store_dword v207, v93, s[44:45] offset:192
	global_store_dword v208, v94, s[44:45] offset:192
	global_store_dword v209, v95, s[44:45] offset:192
	global_store_dword v206, v96, s[46:47]
	global_store_dword v207, v97, s[46:47]
	global_store_dword v208, v98, s[46:47]
	global_store_dword v209, v99, s[46:47]
	global_store_dword v206, v100, s[46:47] offset:64
	global_store_dword v207, v101, s[46:47] offset:64
	global_store_dword v208, v102, s[46:47] offset:64
	global_store_dword v209, v103, s[46:47] offset:64
	global_store_dword v206, v104, s[46:47] offset:128
	global_store_dword v207, v105, s[46:47] offset:128
	global_store_dword v208, v106, s[46:47] offset:128
	global_store_dword v209, v107, s[46:47] offset:128
	global_store_dword v206, v108, s[46:47] offset:192
	global_store_dword v207, v109, s[46:47] offset:192
	global_store_dword v208, v110, s[46:47] offset:192
	global_store_dword v209, v111, s[46:47] offset:192
